# gdnpre block inversion: LDS operand reads issued a block ahead, no filler instructions (operand gaps as one s_nop 9)
# speedup vs baseline: 1.0014x; 1.0014x over previous
.LBB0_275:
	s_or_b64 exec, exec, s[12:13]
	s_waitcnt lgkmcnt(0)
	v_sub_f32_e32 v4, v15, v4
	v_mul_f32_e32 v4, 0x3fb8aa3b, v4
	v_exp_f32_e32 v4, v4
	v_cmp_gt_i32_e64 s[40:41], v10, v48
	v_mul_f32_e32 v11, v6, v11
	v_mul_f32_e32 v17, v7, v23
	v_mul_f32_e32 v22, v8, v22
	v_mul_f32_e32 v15, v7, v20
	v_mul_f32_e32 v20, v6, v21
	v_cndmask_b32_e64 v4, v4, 0, s[40:41]
	v_mul_f32_e32 v6, v9, v3
	v_mul_f32_e32 v8, v8, v24
	v_cvt_pk_bf16_f32 v7, v22, v6
	v_cvt_pk_bf16_f32 v6, v11, v17
	v_mul_f32_e32 v11, v9, v4
	v_cvt_pk_bf16_f32 v8, v11, v8
	v_mul_f32_e32 v11, v5, v13
	v_mul_f32_e32 v3, v11, v3
	v_cndmask_b32_e64 v3, 0, v3, s[40:41]
	ds_write_b32 v2, v3 offset:12
	v_mul_f32_e32 v2, v5, v12
	v_mul_f32_e32 v2, v2, v4
	v_sub_u32_e32 v3, v16, v48
	v_cndmask_b32_e64 v2, 0, v2, s[0:1]
	v_lshl_add_u32 v3, v3, 2, 0
	ds_write_b32 v3, v2 offset:16892
	v_lshlrev_b32_e32 v2, 7, v10
	v_mov_b32_e32 v3, v0
	v_lshl_add_u64 v[4:5], v[30:31], 0, v[2:3]
	v_xor_b32_e32 v2, 0x1f80, v2
	v_cvt_pk_bf16_f32 v9, v15, v20
	v_lshl_add_u64 v[2:3], v[46:47], 0, v[2:3]
	global_store_dwordx2 v[4:5], v[6:7], off
	global_store_dwordx2 v[2:3], v[8:9], off
	s_waitcnt lgkmcnt(0)
	s_barrier
	s_and_saveexec_b64 s[0:1], vcc
	s_cbranch_execz .LBB0_277
	s_movk_i32 s2, 0x4100
	v_mul_lo_u32 v3, v68, s2
	v_add_u32_e32 v4, 0, v3
	v_and_b32_e32 v3, 48, v1
	v_mul_u32_u24_e32 v5, 0x104, v3
	v_lshlrev_b32_e32 v6, 2, v3
	v_add3_u32 v5, v4, v5, v6
	ds_read_b32 v16, v5 offset:260
	ds_read_b64 v[20:21], v5 offset:520
	ds_read_b32 v17, v5 offset:780
	ds_read_b64 v[22:23], v5 offset:784
	ds_read_b128 v[46:49], v5 offset:1040
	ds_read_b32 v24, v5 offset:1300
	ds_read_b64 v[30:31], v5 offset:1304
	ds_read_b64 v[50:51], v5 offset:1312
	ds_read_b64 v[52:53], v5 offset:1560
	ds_read_b128 v[54:57], v5 offset:1568
	ds_read_b32 v25, v5 offset:1820
	ds_read_b128 v[58:61], v5 offset:1824
	ds_read_b64 v[62:63], v5 offset:1840
	ds_read_b128 v[64:67], v5 offset:2080
	ds_read_b128 v[70:73], v5 offset:2096
	ds_read_b32 v74, v5 offset:2340
	ds_read_b64 v[76:77], v5 offset:2344
	ds_read_b128 v[78:81], v5 offset:2352
	ds_read_b64 v[82:83], v5 offset:2368
	ds_read_b64 v[84:85], v5 offset:2600
	ds_read_b128 v[90:93], v5 offset:2608
	ds_read_b128 v[152:155], v5 offset:2624
	ds_read_b32 v75, v5 offset:2860
	ds_read_b128 v[156:159], v5 offset:2864
	ds_read_b128 v[160:163], v5 offset:2880
	ds_read_b64 v[86:87], v5 offset:2896
	ds_read_b128 v[164:167], v5 offset:3120
	ds_read_b128 v[168:171], v5 offset:3136
	ds_read_b128 v[234:237], v5 offset:3152
	ds_read_b32 v88, v5 offset:3380
	ds_read_b64 v[94:95], v5 offset:3384
	ds_read_b128 v[238:241], v5 offset:3392
	ds_read_b128 v[250:253], v5 offset:3408
	ds_read_b64 v[242:243], v5 offset:3424
	v_cmp_eq_u32_e32 vcc, 0, v37
	v_cndmask_b32_e64 v27, 0, 1.0, vcc
	v_cmp_eq_u32_e32 vcc, 1, v37
	s_waitcnt lgkmcnt(15)
	v_cndmask_b32_e64 v33, 0, 1.0, vcc
	v_fma_f32 v33, -v27, v16, v33
	v_cmp_eq_u32_e32 vcc, 2, v37
	s_waitcnt lgkmcnt(15)
	v_cndmask_b32_e64 v39, 0, 1.0, vcc
	v_fma_f32 v39, -v27, v20, v39
	v_fma_f32 v39, -v33, v21, v39
	v_cmp_eq_u32_e32 vcc, 3, v37
	s_waitcnt lgkmcnt(15)
	v_cndmask_b32_e64 v11, 0, 1.0, vcc
	v_fma_f32 v11, -v27, v17, v11
	v_fma_f32 v11, -v33, v22, v11
	v_fma_f32 v11, -v39, v23, v11
	v_cmp_eq_u32_e32 vcc, 4, v37
	s_waitcnt lgkmcnt(15)
	v_cndmask_b32_e64 v15, 0, 1.0, vcc
	v_fma_f32 v15, -v27, v46, v15
	v_fma_f32 v15, -v33, v47, v15
	v_fma_f32 v15, -v39, v48, v15
	v_fma_f32 v15, -v11, v49, v15
	v_cmp_eq_u32_e32 vcc, 5, v37
	s_waitcnt lgkmcnt(15)
	v_cndmask_b32_e64 v29, 0, 1.0, vcc
	v_fma_f32 v29, -v27, v24, v29
	v_fma_f32 v29, -v33, v30, v29
	v_fma_f32 v29, -v39, v31, v29
	v_fma_f32 v29, -v11, v50, v29
	v_fma_f32 v29, -v15, v51, v29
	v_cmp_eq_u32_e32 vcc, 6, v37
	s_waitcnt lgkmcnt(15)
	v_cndmask_b32_e64 v69, 0, 1.0, vcc
	v_fma_f32 v69, -v27, v52, v69
	v_fma_f32 v69, -v33, v53, v69
	v_fma_f32 v69, -v39, v54, v69
	v_fma_f32 v69, -v11, v55, v69
	v_fma_f32 v69, -v15, v56, v69
	v_fma_f32 v69, -v29, v57, v69
	v_cmp_eq_u32_e32 vcc, 7, v37
	s_waitcnt lgkmcnt(15)
	v_cndmask_b32_e64 v151, 0, 1.0, vcc
	v_fma_f32 v151, -v27, v25, v151
	v_fma_f32 v151, -v33, v58, v151
	v_fma_f32 v151, -v39, v59, v151
	v_fma_f32 v151, -v11, v60, v151
	v_fma_f32 v151, -v15, v61, v151
	v_fma_f32 v151, -v29, v62, v151
	v_fma_f32 v151, -v69, v63, v151
	v_cmp_eq_u32_e32 vcc, 8, v37
	s_waitcnt lgkmcnt(15)
	v_cndmask_b32_e64 v233, 0, 1.0, vcc
	v_fma_f32 v233, -v27, v64, v233
	v_fma_f32 v233, -v33, v65, v233
	v_fma_f32 v233, -v39, v66, v233
	v_fma_f32 v233, -v11, v67, v233
	v_fma_f32 v233, -v15, v70, v233
	v_fma_f32 v233, -v29, v71, v233
	v_fma_f32 v233, -v69, v72, v233
	v_fma_f32 v233, -v151, v73, v233
	v_cmp_eq_u32_e32 vcc, 9, v37
	s_waitcnt lgkmcnt(15)
	v_cndmask_b32_e64 v249, 0, 1.0, vcc
	v_fma_f32 v249, -v27, v74, v249
	v_fma_f32 v249, -v33, v76, v249
	v_fma_f32 v249, -v39, v77, v249
	v_fma_f32 v249, -v11, v78, v249
	v_fma_f32 v249, -v15, v79, v249
	v_fma_f32 v249, -v29, v80, v249
	v_fma_f32 v249, -v69, v81, v249
	v_fma_f32 v249, -v151, v82, v249
	v_fma_f32 v249, -v233, v83, v249
	ds_read_b64 v[16:17], v5 offset:3640
	ds_read_b128 v[20:23], v5 offset:3648
	ds_read_b128 v[46:49], v5 offset:3664
	ds_read_b128 v[50:53], v5 offset:3680
	ds_read_b32 v244, v5 offset:3900
	ds_read_b128 v[54:57], v5 offset:3904
	ds_read_b128 v[58:61], v5 offset:3920
	ds_read_b128 v[62:65], v5 offset:3936
	ds_read_b64 v[24:25], v5 offset:3952
	v_cmp_eq_u32_e32 vcc, 10, v37
	s_waitcnt lgkmcnt(15)
	v_cndmask_b32_e64 v6, 0, 1.0, vcc
	v_fma_f32 v6, -v27, v84, v6
	v_fma_f32 v6, -v33, v85, v6
	v_fma_f32 v6, -v39, v90, v6
	v_fma_f32 v6, -v11, v91, v6
	v_fma_f32 v6, -v15, v92, v6
	v_fma_f32 v6, -v29, v93, v6
	v_fma_f32 v6, -v69, v152, v6
	v_fma_f32 v6, -v151, v153, v6
	v_fma_f32 v6, -v233, v154, v6
	v_fma_f32 v6, -v249, v155, v6
	v_cmp_eq_u32_e32 vcc, 11, v37
	s_waitcnt lgkmcnt(15)
	v_cndmask_b32_e64 v7, 0, 1.0, vcc
	v_fma_f32 v7, -v27, v75, v7
	v_fma_f32 v7, -v33, v156, v7
	v_fma_f32 v7, -v39, v157, v7
	v_fma_f32 v7, -v11, v158, v7
	v_fma_f32 v7, -v15, v159, v7
	v_fma_f32 v7, -v29, v160, v7
	v_fma_f32 v7, -v69, v161, v7
	v_fma_f32 v7, -v151, v162, v7
	v_fma_f32 v7, -v233, v163, v7
	v_fma_f32 v7, -v249, v86, v7
	v_fma_f32 v7, -v6, v87, v7
	v_cmp_eq_u32_e32 vcc, 12, v37
	s_waitcnt lgkmcnt(14)
	v_cndmask_b32_e64 v8, 0, 1.0, vcc
	v_fma_f32 v8, -v27, v164, v8
	v_fma_f32 v8, -v33, v165, v8
	v_fma_f32 v8, -v39, v166, v8
	v_fma_f32 v8, -v11, v167, v8
	v_fma_f32 v8, -v15, v168, v8
	v_fma_f32 v8, -v29, v169, v8
	v_fma_f32 v8, -v69, v170, v8
	v_fma_f32 v8, -v151, v171, v8
	v_fma_f32 v8, -v233, v234, v8
	v_fma_f32 v8, -v249, v235, v8
	v_fma_f32 v8, -v6, v236, v8
	v_fma_f32 v8, -v7, v237, v8
	v_cmp_eq_u32_e32 vcc, 13, v37
	s_waitcnt lgkmcnt(9)
	v_cndmask_b32_e64 v9, 0, 1.0, vcc
	v_fma_f32 v9, -v27, v88, v9
	v_fma_f32 v9, -v33, v94, v9
	v_fma_f32 v9, -v39, v95, v9
	v_fma_f32 v9, -v11, v238, v9
	v_fma_f32 v9, -v15, v239, v9
	v_fma_f32 v9, -v29, v240, v9
	v_fma_f32 v9, -v69, v241, v9
	v_fma_f32 v9, -v151, v250, v9
	v_fma_f32 v9, -v233, v251, v9
	v_fma_f32 v9, -v249, v252, v9
	v_fma_f32 v9, -v6, v253, v9
	v_fma_f32 v9, -v7, v242, v9
	v_fma_f32 v9, -v8, v243, v9
	v_cmp_eq_u32_e32 vcc, 14, v37
	s_waitcnt lgkmcnt(5)
	v_cndmask_b32_e64 v12, 0, 1.0, vcc
	v_fma_f32 v12, -v27, v16, v12
	v_fma_f32 v12, -v33, v17, v12
	v_fma_f32 v12, -v39, v20, v12
	v_fma_f32 v12, -v11, v21, v12
	v_fma_f32 v12, -v15, v22, v12
	v_fma_f32 v12, -v29, v23, v12
	v_fma_f32 v12, -v69, v46, v12
	v_fma_f32 v12, -v151, v47, v12
	v_fma_f32 v12, -v233, v48, v12
	v_fma_f32 v12, -v249, v49, v12
	v_fma_f32 v12, -v6, v50, v12
	v_fma_f32 v12, -v7, v51, v12
	v_fma_f32 v12, -v8, v52, v12
	v_fma_f32 v12, -v9, v53, v12
	v_cmp_eq_u32_e32 vcc, 15, v37
	s_waitcnt lgkmcnt(0)
	v_cndmask_b32_e64 v13, 0, 1.0, vcc
	v_fma_f32 v13, -v27, v244, v13
	v_fma_f32 v13, -v33, v54, v13
	v_fma_f32 v13, -v39, v55, v13
	v_fma_f32 v13, -v11, v56, v13
	v_fma_f32 v13, -v15, v57, v13
	v_fma_f32 v13, -v29, v58, v13
	v_fma_f32 v13, -v69, v59, v13
	v_fma_f32 v13, -v151, v60, v13
	v_fma_f32 v13, -v233, v61, v13
	v_fma_f32 v13, -v249, v62, v13
	v_fma_f32 v13, -v6, v63, v13
	v_fma_f32 v13, -v7, v64, v13
	v_fma_f32 v13, -v8, v65, v13
	v_fma_f32 v13, -v9, v24, v13
	v_fma_f32 v13, -v12, v25, v13
	v_add_u32_e32 v5, v5, v41
	ds_write_b32 v5, v27
	ds_write_b32 v5, v33 offset:260
	ds_write_b32 v5, v39 offset:520
	ds_write_b32 v5, v11 offset:780
	ds_write_b32 v5, v15 offset:1040
	ds_write_b32 v5, v29 offset:1300
	ds_write_b32 v5, v69 offset:1560
	ds_write_b32 v5, v151 offset:1820
	ds_write_b32 v5, v233 offset:2080
	ds_write_b32 v5, v249 offset:2340
	ds_write_b32 v5, v6 offset:2600
	ds_write_b32 v5, v7 offset:2860
	ds_write_b32 v5, v8 offset:3120
	ds_write_b32 v5, v9 offset:3380
	ds_write_b32 v5, v12 offset:3640
	ds_write_b32 v5, v13 offset:3900
	v_mul_u32_u24_e32 v2, 0x104, v37
	s_movk_i32 s2, 0x1040
	v_add3_u32 v2, v2, v4, s2
	s_movk_i32 s2, 0x104
	v_add_u32_e32 v5, v4, v41
	v_lshl_add_u32 v4, v45, 2, v2
	ds_read2_b32 v[152:153], v4 offset1:4
	ds_read2_b32 v[154:155], v4 offset0:8 offset1:12
	v_add_u32_e32 v11, v2, v3
	ds_read2_b32 v[156:157], v11 offset0:16 offset1:17
	ds_read2_b32 v[158:159], v11 offset0:18 offset1:19
	v_mad_u32_u24 v2, v45, s2, v5
	ds_read_b32 v233, v2
	ds_read_b32 v244, v2 offset:1040
	ds_read_b32 v249, v2 offset:2080
	ds_read_b32 v160, v2 offset:3120
	s_waitcnt lgkmcnt(3)
	v_mfma_f32_16x16x4_f32 v[6:9], v152, v233, 0
	s_movk_i32 s2, 0x410
	v_mad_u32_u24 v3, v45, s2, v5
	v_add_u32_e32 v48, 0x2140, v11
	s_waitcnt lgkmcnt(2)
	v_mfma_f32_16x16x4_f32 v[6:9], v153, v244, v[6:9]
	s_waitcnt lgkmcnt(1)
	v_mfma_f32_16x16x4_f32 v[6:9], v154, v249, v[6:9]
	s_waitcnt lgkmcnt(0)
	v_mfma_f32_16x16x4_f32 v[6:9], v155, v160, v[6:9]
	s_nop 9
	v_mfma_f32_16x16x4_f32 v[20:23], v156, v6, 0
	v_mfma_f32_16x16x4_f32 v[20:23], v157, v7, v[20:23]
	v_mfma_f32_16x16x4_f32 v[20:23], v158, v8, v[20:23]
	v_mfma_f32_16x16x4_f32 v[6:9], v159, v9, v[20:23]
	s_nop 9
	v_xor_b32_e32 v6, 0x80000000, v6
	v_xor_b32_e32 v5, 0x80000000, v7
	v_add_u32_e32 v7, 0x1000, v3
	ds_write2_b32 v7, v6, v5 offset0:16 offset1:81
	v_xor_b32_e32 v5, 0x80000000, v8
	v_xor_b32_e32 v6, 0x80000000, v9
	ds_write2_b32 v7, v5, v6 offset0:146 offset1:211
	ds_read_b32 v161, v4 offset:4224
	ds_read_b32 v152, v2 offset:4160
	ds_read_b32 v153, v4 offset:4240
	ds_read_b32 v154, v2 offset:5200
	ds_read_b32 v155, v4 offset:4256
	ds_read_b32 v156, v2 offset:6240
	ds_read_b32 v157, v4 offset:4272
	ds_read_b32 v158, v2 offset:7280
	v_add_u32_e32 v6, 0x1000, v4
	ds_read2_b32 v[162:163], v6 offset0:16 offset1:20
	ds_read2_b32 v[164:165], v6 offset0:24 offset1:28
	s_waitcnt lgkmcnt(1)
	v_mfma_f32_16x16x4_f32 v[6:9], v162, v233, 0
	v_add_u32_e32 v5, 0x10c0, v11
	ds_read2_b32 v[166:167], v5 offset1:1
	v_mfma_f32_16x16x4_f32 v[6:9], v163, v244, v[6:9]
	s_waitcnt lgkmcnt(1)
	v_mfma_f32_16x16x4_f32 v[6:9], v164, v249, v[6:9]
	v_add_u32_e32 v16, 0x10c8, v11
	ds_read2_b32 v[162:163], v16 offset1:1
	v_add_u32_e32 v11, 0x2148, v11
	v_mfma_f32_16x16x4_f32 v[6:9], v165, v160, v[6:9]
	v_mfma_f32_16x16x4_f32 v[6:9], v161, v152, v[6:9]
	v_mfma_f32_16x16x4_f32 v[6:9], v153, v154, v[6:9]
	v_mfma_f32_16x16x4_f32 v[6:9], v155, v156, v[6:9]
	v_mfma_f32_16x16x4_f32 v[6:9], v157, v158, v[6:9]
	s_nop 9
	s_waitcnt lgkmcnt(1)
	v_mfma_f32_16x16x4_f32 v[20:23], v166, v6, 0
	v_mfma_f32_16x16x4_f32 v[20:23], v167, v7, v[20:23]
	s_waitcnt lgkmcnt(0)
	v_mfma_f32_16x16x4_f32 v[20:23], v162, v8, v[20:23]
	v_mfma_f32_16x16x4_f32 v[6:9], v163, v9, v[20:23]
	s_nop 9
	v_xor_b32_e32 v6, 0x80000000, v6
	ds_write_b32 v3, v6 offset:8320
	v_xor_b32_e32 v6, 0x80000000, v7
	ds_write_b32 v3, v6 offset:8580
	v_xor_b32_e32 v6, 0x80000000, v8
	ds_write_b32 v3, v6 offset:8840
	v_xor_b32_e32 v6, 0x80000000, v9
	ds_write_b32 v3, v6 offset:9100
	ds_read_b32 v153, v2 offset:4224
	ds_read_b32 v155, v4 offset:4224
	ds_read_b32 v157, v4 offset:4240
	ds_read_b32 v159, v4 offset:4256
	ds_read_b32 v161, v4 offset:4272
	ds_read_b32 v162, v2 offset:5264
	ds_read_b32 v163, v2 offset:6304
	ds_read_b32 v164, v2 offset:7344
	ds_read2_b32 v[166:167], v5 offset1:1
	ds_read2_b32 v[168:169], v16 offset1:1
	s_waitcnt lgkmcnt(8)
	v_mfma_f32_16x16x4_f32 v[6:9], v155, v153, 0
	s_waitcnt lgkmcnt(4)
	v_mfma_f32_16x16x4_f32 v[6:9], v157, v162, v[6:9]
	s_waitcnt lgkmcnt(3)
	v_mfma_f32_16x16x4_f32 v[6:9], v159, v163, v[6:9]
	s_waitcnt lgkmcnt(2)
	v_mfma_f32_16x16x4_f32 v[6:9], v161, v164, v[6:9]
	s_nop 9
	s_waitcnt lgkmcnt(1)
	v_mfma_f32_16x16x4_f32 v[20:23], v166, v6, 0
	v_mfma_f32_16x16x4_f32 v[20:23], v167, v7, v[20:23]
	s_waitcnt lgkmcnt(0)
	v_mfma_f32_16x16x4_f32 v[20:23], v168, v8, v[20:23]
	v_mfma_f32_16x16x4_f32 v[6:9], v169, v9, v[20:23]
	s_nop 9
	v_xor_b32_e32 v5, 0x80000000, v6
	ds_write_b32 v3, v5 offset:8384
	v_xor_b32_e32 v5, 0x80000000, v7
	ds_write_b32 v3, v5 offset:8644
	v_xor_b32_e32 v5, 0x80000000, v8
	ds_write_b32 v3, v5 offset:8904
	v_xor_b32_e32 v5, 0x80000000, v9
	ds_write_b32 v3, v5 offset:9164
	ds_read_b32 v155, v4 offset:8384
	ds_read_b32 v157, v4 offset:8400
	ds_read_b32 v159, v4 offset:8416
	ds_read_b32 v161, v4 offset:8432
	ds_read_b32 v165, v4 offset:8448
	ds_read_b32 v166, v2 offset:8320
	ds_read_b32 v167, v4 offset:8464
	ds_read_b32 v168, v2 offset:9360
	ds_read_b32 v169, v4 offset:8480
	ds_read_b32 v170, v2 offset:10400
	ds_read_b32 v171, v4 offset:8496
	ds_read_b32 v234, v2 offset:11440
	ds_read2_b32 v[236:237], v48 offset1:1
	ds_read2_b32 v[238:239], v11 offset1:1
	v_add_u32_e32 v5, 0x2000, v4
	ds_read2_b32 v[240:241], v5 offset0:32 offset1:36
	ds_read2_b32 v[242:243], v5 offset0:40 offset1:44
	s_waitcnt lgkmcnt(1)
	v_mfma_f32_16x16x4_f32 v[6:9], v240, v233, 0
	v_mfma_f32_16x16x4_f32 v[6:9], v241, v244, v[6:9]
	s_waitcnt lgkmcnt(0)
	v_mfma_f32_16x16x4_f32 v[6:9], v242, v249, v[6:9]
	v_mfma_f32_16x16x4_f32 v[6:9], v243, v160, v[6:9]
	v_mfma_f32_16x16x4_f32 v[6:9], v155, v152, v[6:9]
	v_mfma_f32_16x16x4_f32 v[6:9], v157, v154, v[6:9]
	v_mfma_f32_16x16x4_f32 v[6:9], v159, v156, v[6:9]
	v_mfma_f32_16x16x4_f32 v[6:9], v161, v158, v[6:9]
	v_mfma_f32_16x16x4_f32 v[6:9], v165, v166, v[6:9]
	v_mfma_f32_16x16x4_f32 v[6:9], v167, v168, v[6:9]
	v_mfma_f32_16x16x4_f32 v[6:9], v169, v170, v[6:9]
	v_mfma_f32_16x16x4_f32 v[6:9], v171, v234, v[6:9]
	s_nop 9
	v_mfma_f32_16x16x4_f32 v[20:23], v236, v6, 0
	v_mfma_f32_16x16x4_f32 v[20:23], v237, v7, v[20:23]
	v_mfma_f32_16x16x4_f32 v[20:23], v238, v8, v[20:23]
	v_mfma_f32_16x16x4_f32 v[6:9], v239, v9, v[20:23]
	s_nop 9
	v_xor_b32_e32 v5, 0x80000000, v6
	ds_write_b32 v3, v5 offset:12480
	v_xor_b32_e32 v5, 0x80000000, v7
	ds_write_b32 v3, v5 offset:12740
	v_xor_b32_e32 v5, 0x80000000, v8
	ds_write_b32 v3, v5 offset:13000
	v_xor_b32_e32 v5, 0x80000000, v9
	ds_write_b32 v3, v5 offset:13260
	ds_read_b32 v152, v4 offset:8384
	ds_read_b32 v165, v4 offset:8400
	ds_read_b32 v233, v4 offset:8416
	ds_read_b32 v244, v4 offset:8432
	ds_read_b32 v249, v4 offset:8448
	ds_read_b32 v154, v2 offset:8384
	ds_read_b32 v155, v4 offset:8464
	ds_read_b32 v156, v2 offset:9424
	ds_read_b32 v157, v4 offset:8480
	ds_read_b32 v158, v2 offset:10464
	ds_read_b32 v159, v4 offset:8496
	ds_read_b32 v160, v2 offset:11504
	ds_read2_b32 v[166:167], v48 offset1:1
	ds_read2_b32 v[168:169], v11 offset1:1
	s_waitcnt lgkmcnt(13)
	v_mfma_f32_16x16x4_f32 v[6:9], v152, v153, 0
	s_waitcnt lgkmcnt(12)
	v_mfma_f32_16x16x4_f32 v[6:9], v165, v162, v[6:9]
	s_waitcnt lgkmcnt(11)
	v_mfma_f32_16x16x4_f32 v[6:9], v233, v163, v[6:9]
	s_waitcnt lgkmcnt(10)
	v_mfma_f32_16x16x4_f32 v[6:9], v244, v164, v[6:9]
	s_waitcnt lgkmcnt(8)
	v_mfma_f32_16x16x4_f32 v[6:9], v249, v154, v[6:9]
	s_waitcnt lgkmcnt(6)
	v_mfma_f32_16x16x4_f32 v[6:9], v155, v156, v[6:9]
	s_waitcnt lgkmcnt(4)
	v_mfma_f32_16x16x4_f32 v[6:9], v157, v158, v[6:9]
	s_waitcnt lgkmcnt(2)
	v_mfma_f32_16x16x4_f32 v[6:9], v159, v160, v[6:9]
	s_nop 9
	s_waitcnt lgkmcnt(1)
	v_mfma_f32_16x16x4_f32 v[20:23], v166, v6, 0
	v_mfma_f32_16x16x4_f32 v[20:23], v167, v7, v[20:23]
	s_waitcnt lgkmcnt(0)
	v_mfma_f32_16x16x4_f32 v[20:23], v168, v8, v[20:23]
	v_mfma_f32_16x16x4_f32 v[6:9], v169, v9, v[20:23]
	s_nop 9
	v_xor_b32_e32 v5, 0x80000000, v6
	ds_write_b32 v3, v5 offset:12544
	v_xor_b32_e32 v5, 0x80000000, v7
	ds_write_b32 v3, v5 offset:12804
	v_xor_b32_e32 v5, 0x80000000, v8
	ds_write_b32 v3, v5 offset:13064
	v_xor_b32_e32 v5, 0x80000000, v9
	ds_write_b32 v3, v5 offset:13324
	ds_read_b32 v233, v2 offset:8448
	ds_read_b32 v244, v4 offset:8448
	ds_read_b32 v249, v4 offset:8464
	ds_read_b32 v152, v4 offset:8480
	ds_read_b32 v153, v4 offset:8496
	ds_read_b32 v154, v2 offset:9488
	ds_read_b32 v155, v2 offset:10528
	ds_read_b32 v156, v2 offset:11568
	ds_read2_b32 v[158:159], v48 offset1:1
	ds_read2_b32 v[160:161], v11 offset1:1
	s_waitcnt lgkmcnt(8)
	v_mfma_f32_16x16x4_f32 v[4:7], v244, v233, 0
	s_waitcnt lgkmcnt(4)
	v_mfma_f32_16x16x4_f32 v[4:7], v249, v154, v[4:7]
	s_waitcnt lgkmcnt(3)
	v_mfma_f32_16x16x4_f32 v[4:7], v152, v155, v[4:7]
	s_waitcnt lgkmcnt(2)
	v_mfma_f32_16x16x4_f32 v[4:7], v153, v156, v[4:7]
	s_nop 9
	s_waitcnt lgkmcnt(1)
	v_mfma_f32_16x16x4_f32 v[20:23], v158, v4, 0
	v_mfma_f32_16x16x4_f32 v[20:23], v159, v5, v[20:23]
	s_waitcnt lgkmcnt(0)
	v_mfma_f32_16x16x4_f32 v[20:23], v160, v6, v[20:23]
	v_mfma_f32_16x16x4_f32 v[4:7], v161, v7, v[20:23]
	s_nop 9
	v_xor_b32_e32 v2, 0x80000000, v4
	ds_write_b32 v3, v2 offset:12608
	v_xor_b32_e32 v2, 0x80000000, v5
	ds_write_b32 v3, v2 offset:12868
	v_xor_b32_e32 v2, 0x80000000, v6
	ds_write_b32 v3, v2 offset:13128
	v_xor_b32_e32 v2, 0x80000000, v7
	ds_write_b32 v3, v2 offset:13388
